# int8 merge-gate epilogue of the input projection: its 16 operand loads issued in one batch (hipcc had 5 dependent round trips), copied back at the original wait points
# speedup vs baseline: 1.0097x; 1.0058x over previous
;     __device__ __forceinline__ void operator()(f32x4 (&acc)[2][2][4][2], const Unit& u, int wr, int wc, int fr, int fq) const {
;     ...
;         if (mode == 3) {
;             f32x4 cn[4], bn[4];
; #pragma unroll
;             for (int k = 0; k < 4; ++k) { const u32x4 c_ = *(const u32x4*)(cmax + col0 + (k >> 1) * CBJ + (k & 1) * 4); const f32x4 b_ = *(const f32x4*)(bgate + (col0 + C_I8 - C_GT) + (k >> 1) * CBJ + (k & 1) * 4);
; #pragma unroll
;                 for (int j = 0; j < 4; ++j) { cn[k][j] = __uint_as_float(c_[j]) * -LOG2E; bn[k][j] = b_[j] * -LOG2E; } }
;             float sv[8];
; #pragma unroll
;             for (int k = 0; k < 8; ++k) sv[k] = sa[rowg + (k >> 2) * HALF + (k & 3) * 16 + fr] * (1.0f / 127.0f);
; #pragma unroll
;             for (int ai = 0; ai < 2; ++ai)
; #pragma unroll
;                 for (int m = 0; m < 4; ++m) {
;                     const float s = sv[ai * 4 + m];
;                     u32x2 gb[2];
; #pragma unroll
;                     for (int bj = 0; bj < 2; ++bj) {
;                         const v4i_t i0 = __builtin_bit_cast(v4i_t, acc[ai][bj][m][0]), i1 = __builtin_bit_cast(v4i_t, acc[ai][bj][m][1]);
;                         unsigned w0 = 0u, w1 = 0u;
; #pragma unroll
;                         for (int j = 0; j < 4; ++j) {
;                             const float e0 = __builtin_amdgcn_exp2f(__builtin_fmaf((float)i0[j], s * cn[bj * 2][j], bn[bj * 2][j])), e1 = __builtin_amdgcn_exp2f(__builtin_fmaf((float)i1[j], s * cn[bj * 2 + 1][j], bn[bj * 2 + 1][j]));
;                             const float g0 = __builtin_amdgcn_rcpf(__builtin_fmaf(e0, 1.0f / 255.0f, 1.0f / 255.0f)), g1 = __builtin_amdgcn_rcpf(__builtin_fmaf(e1, 1.0f / 255.0f, 1.0f / 255.0f));
;                             w0 = __builtin_amdgcn_cvt_pk_u8_f32(fmaxf(g0, 1.0f), j, w0); w1 = __builtin_amdgcn_cvt_pk_u8_f32(fmaxf(g1, 1.0f), j, w1);
;                         }
.LBB0_544:
	s_andn2_b64 vcc, exec, s[6:7]
	v_readlane_b32 s34, v255, 27
	v_readlane_b32 s38, v255, 30
	s_mov_b32 s24, 0x10000
	v_readlane_b32 s35, v255, 28
	s_cbranch_vccnz .LBB0_546
	v_lshlrev_b64 v[52:53], 2, v[168:169]
	v_lshl_add_u64 v[56:57], s[16:17], 0, v[52:53]
	v_lshl_add_u64 v[198:199], s[56:57], 0, v[52:53]
	global_load_dwordx4 v[52:55], v[56:57], off offset:16
	global_load_dwordx4 v[70:73], v[56:57], off
	global_load_dwordx4 v[78:81], v[198:199], off offset:-4080
	global_load_dwordx4 v[168:171], v[198:199], off offset:-4096
	v_readlane_b32 s0, v249, 57
	v_readlane_b32 s1, v249, 58
	global_load_dwordx4 v[194:197], v[56:57], off offset:128
	global_load_dwordx4 v[200:203], v[56:57], off offset:144
	global_load_dwordx4 v[212:215], v[198:199], off offset:-3952
	global_load_dwordx4 v[216:219], v[198:199], off offset:-3968
	v_lshl_add_u64 v[220:221], v[50:51], 2, s[0:1]
	v_add_u32_e32 v230, s14, v177
	v_ashrrev_i32_e32 v231, 31, v230
	v_lshl_add_u64 v[230:231], v[230:231], 2, s[0:1]
	global_load_dword v222, v[220:221], off
	global_load_dword v223, v[220:221], off offset:64
	global_load_dword v224, v[220:221], off offset:128
	global_load_dword v225, v[220:221], off offset:192
	global_load_dword v226, v[230:231], off
	global_load_dword v227, v[230:231], off offset:64
	global_load_dword v228, v[230:231], off offset:128
	global_load_dword v229, v[230:231], off offset:192
	s_mov_b32 s6, 0xbfb8aa3b
	s_mov_b32 s7, 0x3c010204
	v_cvt_f32_i32_e32 v38, v38
	v_cvt_f32_i32_e32 v34, v34
	v_cvt_f32_i32_e32 v39, v39
	v_cvt_f32_i32_e32 v35, v35
	v_cvt_f32_i32_e32 v36, v36
	v_cvt_f32_i32_e32 v37, v37
	s_add_i32 s3, s3, -4
	v_cvt_f32_i32_e32 v30, v30
	v_cvt_f32_i32_e32 v26, v26
	v_cvt_f32_i32_e32 v31, v31
	v_cvt_f32_i32_e32 v27, v27
	v_cvt_f32_i32_e32 v28, v28
	v_cvt_f32_i32_e32 v29, v29
	v_cvt_f32_i32_e32 v22, v22
	v_cvt_f32_i32_e32 v18, v18
	v_cvt_f32_i32_e32 v23, v23
	v_cvt_f32_i32_e32 v19, v19
	v_cvt_f32_i32_e32 v20, v20
	v_cvt_f32_i32_e32 v21, v21
	v_cvt_f32_i32_e32 v14, v14
	v_cvt_f32_i32_e32 v10, v10
	v_cvt_f32_i32_e32 v15, v15
	v_cvt_f32_i32_e32 v11, v11
	v_cvt_f32_i32_e32 v12, v12
	v_cvt_f32_i32_e32 v13, v13
	v_cvt_f32_i32_e32 v6, v6
	v_cvt_f32_i32_e32 v2, v2
	v_cvt_f32_i32_e32 v7, v7
	v_cvt_f32_i32_e32 v3, v3
	v_cvt_f32_i32_e32 v4, v4
	v_cvt_f32_i32_e32 v5, v5
	s_waitcnt vmcnt(12)
	v_mul_f32_e32 v181, 0xbfb8aa3b, v54
	v_mul_f32_e32 v192, 0xbfb8aa3b, v70
	v_mul_f32_e32 v188, 0xbfb8aa3b, v71
	v_mul_f32_e32 v183, 0xbfb8aa3b, v72
	v_mul_f32_e32 v176, 0xbfb8aa3b, v73
	v_mul_f32_e32 v173, 0xbfb8aa3b, v171
	v_mul_f32_e32 v189, 0xbfb8aa3b, v78
	v_mul_f32_e32 v185, 0xbfb8aa3b, v79
	v_mul_f32_e32 v180, 0xbfb8aa3b, v80
	v_mul_f32_e32 v172, 0xbfb8aa3b, v55
	v_mul_f32_e32 v171, 0xbfb8aa3b, v81
	s_nop 0
	s_nop 0
	v_mul_f32_e32 v191, 0xbfb8aa3b, v168
	v_mul_f32_e32 v190, 0xbfb8aa3b, v52
	v_mul_f32_e32 v186, 0xbfb8aa3b, v53
	v_mul_f32_e32 v187, 0xbfb8aa3b, v169
	v_mul_f32_e32 v182, 0xbfb8aa3b, v170
	s_waitcnt vmcnt(9)
	v_mov_b32_e32 v54, v200
	v_mov_b32_e32 v55, v201
	v_mov_b32_e32 v56, v202
	v_mov_b32_e32 v57, v203
	v_mov_b32_e32 v70, v212
	v_mov_b32_e32 v71, v213
	v_mov_b32_e32 v72, v214
	v_mov_b32_e32 v73, v215
	v_mul_f32_e32 v168, 0xbfb8aa3b, v72
	v_mul_f32_e32 v149, 0xbfb8aa3b, v73
	v_lshl_add_u64 v[72:73], v[50:51], 2, s[0:1]
	v_mov_b32_e32 v50, v57
	s_waitcnt vmcnt(8)
	v_mov_b32_e32 v78, v216
	v_mov_b32_e32 v79, v217
	v_mov_b32_e32 v80, v218
	v_mov_b32_e32 v81, v219
	v_mul_f32_e32 v184, 0xbfb8aa3b, v78
	v_mul_f32_e32 v174, 0xbfb8aa3b, v79
	v_mul_f32_e32 v169, 0xbfb8aa3b, v80
	v_mul_f32_e32 v151, 0xbfb8aa3b, v81
	v_mul_f32_e32 v178, 0xbfb8aa3b, v70
	v_mul_f32_e32 v170, 0xbfb8aa3b, v71
	v_mov_b32_e32 v80, v195
	s_waitcnt vmcnt(6)
	v_mov_b32_e32 v51, v222
	v_mov_b32_e32 v57, v223
	v_pk_mul_f32 v[52:53], v[56:57], s[6:7]
	v_mov_b32_e32 v56, v55
	s_waitcnt vmcnt(5)
	v_mov_b32_e32 v57, v224
	v_pk_mul_f32 v[70:71], v[56:57], s[6:7]
	v_mov_b32_e32 v56, v197
	s_waitcnt vmcnt(4)
	v_mov_b32_e32 v55, v225
	v_pk_mul_f32 v[78:79], v[54:55], s[6:7]
	v_add_u32_e32 v54, s14, v177
	v_ashrrev_i32_e32 v55, 31, v54
	v_lshl_add_u64 v[54:55], v[54:55], 2, s[0:1]
	v_pk_mul_f32 v[50:51], v[50:51], s[6:7]
	s_mul_hi_i32 s1, s2, 24
	v_mul_f32_e32 v193, v192, v51
	v_fma_f32 v166, v166, v193, v191
	v_mul_f32_e32 v193, v190, v51
	v_fma_f32 v164, v164, v193, v189
	v_mul_f32_e32 v193, v188, v51
	v_fma_f32 v167, v167, v193, v187
	v_mul_f32_e32 v193, v186, v51
	v_exp_f32_e32 v164, v164
	v_fma_f32 v165, v165, v193, v185
	v_exp_f32_e32 v165, v165
	v_exp_f32_e32 v166, v166
	v_fmamk_f32 v164, v164, 0x3b808081, v244
	v_rcp_f32_e32 v164, v164
	v_fmamk_f32 v165, v165, 0x3b808081, v244
	v_rcp_f32_e32 v165, v165
	v_exp_f32_e32 v167, v167
	v_max_f32_e32 v164, 1.0, v164
	v_cvt_pk_u8_f32 v164, v164, 0, 0
	v_max_f32_e32 v165, 1.0, v165
	v_cvt_pk_u8_f32 v164, v165, 1, v164
	v_mul_f32_e32 v165, v183, v51
	v_fma_f32 v162, v162, v165, v182
	v_mul_f32_e32 v165, v181, v51
	v_fma_f32 v160, v160, v165, v180
	v_exp_f32_e32 v160, v160
	v_exp_f32_e32 v162, v162
	v_fmamk_f32 v166, v166, 0x3b808081, v244
	v_rcp_f32_e32 v166, v166
	v_fmamk_f32 v160, v160, 0x3b808081, v244
	v_rcp_f32_e32 v160, v160
	v_fmamk_f32 v167, v167, 0x3b808081, v244
	v_rcp_f32_e32 v167, v167
	v_fmamk_f32 v162, v162, 0x3b808081, v244
	v_max_f32_e32 v160, 1.0, v160
	v_cvt_pk_u8_f32 v164, v160, 2, v164
	v_mul_f32_e32 v160, v176, v51
	v_fma_f32 v160, v163, v160, v173
	v_exp_f32_e32 v160, v160
	v_rcp_f32_e32 v162, v162
	v_max_f32_e32 v166, 1.0, v166
	v_cvt_pk_u8_f32 v166, v166, 0, 0
	v_fmamk_f32 v160, v160, 0x3b808081, v244
	v_rcp_f32_e32 v160, v160
	v_max_f32_e32 v167, 1.0, v167
	v_cvt_pk_u8_f32 v166, v167, 1, v166
	v_max_f32_e32 v162, 1.0, v162
	v_cvt_pk_u8_f32 v162, v162, 2, v166
	v_max_f32_e32 v160, 1.0, v160
	v_cvt_pk_u8_f32 v160, v160, 3, v162
	v_mul_f32_e32 v163, v172, v51
	v_fma_f32 v161, v161, v163, v171
	v_exp_f32_e32 v161, v161
	s_mul_i32 s2, s2, 24
	v_fmamk_f32 v161, v161, 0x3b808081, v244
	v_rcp_f32_e32 v161, v161
	s_waitcnt vmcnt(3)
;     __device__ __forceinline__ void operator()(f32x4 (&acc)[2][2][4][2], const Unit& u, int wr, int wc, int fr, int fq) const {
;     ...
;                     const float s = sv[ai * 4 + m];
;                     u32x2 gb[2];
; #pragma unroll
;                     for (int bj = 0; bj < 2; ++bj) {
;                         const v4i_t i0 = __builtin_bit_cast(v4i_t, acc[ai][bj][m][0]), i1 = __builtin_bit_cast(v4i_t, acc[ai][bj][m][1]);
;                         unsigned w0 = 0u, w1 = 0u;
; #pragma unroll
;                         for (int j = 0; j < 4; ++j) {
;                             const float e0 = __builtin_amdgcn_exp2f(__builtin_fmaf((float)i0[j], s * cn[bj * 2][j], bn[bj * 2][j])), e1 = __builtin_amdgcn_exp2f(__builtin_fmaf((float)i1[j], s * cn[bj * 2 + 1][j], bn[bj * 2 + 1][j]));
;                             const float g0 = __builtin_amdgcn_rcpf(__builtin_fmaf(e0, 1.0f / 255.0f, 1.0f / 255.0f)), g1 = __builtin_amdgcn_rcpf(__builtin_fmaf(e1, 1.0f / 255.0f, 1.0f / 255.0f));
;                             w0 = __builtin_amdgcn_cvt_pk_u8_f32(fmaxf(g0, 1.0f), j, w0); w1 = __builtin_amdgcn_cvt_pk_u8_f32(fmaxf(g1, 1.0f), j, w1);
;                         }
	v_mov_b32_e32 v57, v226
	v_pk_mul_f32 v[56:57], v[56:57], s[6:7]
	s_waitcnt vmcnt(2)
	v_mov_b32_e32 v197, v227
	v_pk_mul_f32 v[72:73], v[196:197], s[6:7]
	s_waitcnt vmcnt(1)
	v_mov_b32_e32 v81, v228
	v_pk_mul_f32 v[80:81], v[80:81], s[6:7]
	s_waitcnt vmcnt(0)
	v_mov_b32_e32 v195, v229
	v_pk_mul_f32 v[54:55], v[194:195], s[6:7]
	s_ashr_i32 s6, s3, 31
	v_mul_f32_e32 v162, v54, v51
	v_fma_f32 v158, v158, v162, v184
	v_mul_f32_e32 v162, v78, v51
	v_fma_f32 v156, v156, v162, v178
	v_mul_f32_e32 v162, v80, v51
	v_fma_f32 v159, v159, v162, v174
	v_mul_f32_e32 v162, v70, v51
	v_exp_f32_e32 v156, v156
	v_fma_f32 v157, v157, v162, v170
	v_exp_f32_e32 v157, v157
	v_exp_f32_e32 v158, v158
	v_fmamk_f32 v156, v156, 0x3b808081, v244
	v_rcp_f32_e32 v156, v156
	v_fmamk_f32 v157, v157, 0x3b808081, v244
	v_rcp_f32_e32 v157, v157
	v_exp_f32_e32 v159, v159
	v_max_f32_e32 v156, 1.0, v156
	v_cvt_pk_u8_f32 v156, v156, 0, 0
	v_max_f32_e32 v157, 1.0, v157
	v_cvt_pk_u8_f32 v156, v157, 1, v156
	v_mul_f32_e32 v157, v72, v51
	v_fma_f32 v154, v154, v157, v169
	v_mul_f32_e32 v157, v52, v51
	v_fma_f32 v152, v152, v157, v168
	v_exp_f32_e32 v152, v152
	v_exp_f32_e32 v154, v154
	v_fmamk_f32 v158, v158, 0x3b808081, v244
	v_rcp_f32_e32 v158, v158
	v_fmamk_f32 v152, v152, 0x3b808081, v244
	v_rcp_f32_e32 v152, v152
	v_fmamk_f32 v159, v159, 0x3b808081, v244
	v_rcp_f32_e32 v159, v159
	v_fmamk_f32 v154, v154, 0x3b808081, v244
	v_max_f32_e32 v152, 1.0, v152
	v_cvt_pk_u8_f32 v152, v152, 2, v156
	v_mul_f32_e32 v156, v56, v51
	v_mul_f32_e32 v51, v50, v51
	v_fma_f32 v51, v153, v51, v149
	v_exp_f32_e32 v51, v51
	v_fma_f32 v155, v155, v156, v151
	v_exp_f32_e32 v155, v155
	v_rcp_f32_e32 v154, v154
	v_fmamk_f32 v51, v51, 0x3b808081, v244
	v_rcp_f32_e32 v51, v51
	v_fmamk_f32 v153, v155, 0x3b808081, v244
	s_add_u32 s0, s2, s3
	v_rcp_f32_e32 v153, v153
	v_max_f32_e32 v51, 1.0, v51
	v_cvt_pk_u8_f32 v155, v51, 3, v152
	v_mul_f32_e32 v51, v192, v53
	v_fma_f32 v51, v128, v51, v191
	v_mul_f32_e32 v128, v190, v53
	v_fma_f32 v126, v126, v128, v189
	v_mul_f32_e32 v128, v188, v53
	v_fma_f32 v128, v129, v128, v187
	v_mul_f32_e32 v129, v186, v53
	v_exp_f32_e32 v126, v126
	v_fma_f32 v127, v127, v129, v185
	v_exp_f32_e32 v127, v127
	v_exp_f32_e32 v51, v51
	v_fmamk_f32 v126, v126, 0x3b808081, v244
	v_rcp_f32_e32 v126, v126
	v_fmamk_f32 v127, v127, 0x3b808081, v244
	v_rcp_f32_e32 v127, v127
	v_exp_f32_e32 v128, v128
	v_max_f32_e32 v126, 1.0, v126
	v_cvt_pk_u8_f32 v126, v126, 0, 0
	v_max_f32_e32 v127, 1.0, v127
	v_cvt_pk_u8_f32 v126, v127, 1, v126
	v_mul_f32_e32 v127, v183, v53
	v_fma_f32 v124, v124, v127, v182
	v_mul_f32_e32 v127, v181, v53
	v_fma_f32 v122, v122, v127, v180
	v_exp_f32_e32 v124, v124
	v_exp_f32_e32 v122, v122
	v_fmamk_f32 v51, v51, 0x3b808081, v244
	v_rcp_f32_e32 v51, v51
	v_fmamk_f32 v128, v128, 0x3b808081, v244
	v_rcp_f32_e32 v128, v128
	v_fmamk_f32 v124, v124, 0x3b808081, v244
	v_fmamk_f32 v122, v122, 0x3b808081, v244
	v_rcp_f32_e32 v124, v124
	v_rcp_f32_e32 v122, v122
	v_max_f32_e32 v51, 1.0, v51
	v_cvt_pk_u8_f32 v51, v51, 0, 0
	v_max_f32_e32 v128, 1.0, v128
	v_cvt_pk_u8_f32 v51, v128, 1, v51
	v_max_f32_e32 v124, 1.0, v124
	v_max_f32_e32 v122, 1.0, v122
	v_cvt_pk_u8_f32 v51, v124, 2, v51
	v_cvt_pk_u8_f32 v124, v122, 2, v126
	v_mul_f32_e32 v122, v176, v53
	v_fma_f32 v122, v125, v122, v173
	v_mul_f32_e32 v125, v172, v53
	v_exp_f32_e32 v122, v122
	v_fma_f32 v123, v123, v125, v171
	v_exp_f32_e32 v123, v123
	s_addc_u32 s1, s1, s6
	v_fmamk_f32 v122, v122, 0x3b808081, v244
	v_rcp_f32_e32 v122, v122
	v_fmamk_f32 v123, v123, 0x3b808081, v244
	v_rcp_f32_e32 v123, v123
	v_max_f32_e32 v158, 1.0, v158
	v_max_f32_e32 v122, 1.0, v122
	v_cvt_pk_u8_f32 v122, v122, 3, v51
	v_max_f32_e32 v51, 1.0, v123
	v_cvt_pk_u8_f32 v123, v51, 3, v124
	v_mul_f32_e32 v51, v54, v53
	v_fma_f32 v51, v120, v51, v184
	v_mul_f32_e32 v120, v78, v53
	v_fma_f32 v118, v118, v120, v178
	v_mul_f32_e32 v120, v80, v53
	v_fma_f32 v120, v121, v120, v174
	v_mul_f32_e32 v121, v70, v53
	v_exp_f32_e32 v118, v118
	v_fma_f32 v119, v119, v121, v170
	v_exp_f32_e32 v119, v119
	v_exp_f32_e32 v51, v51
	v_fmamk_f32 v118, v118, 0x3b808081, v244
	v_rcp_f32_e32 v118, v118
	v_fmamk_f32 v119, v119, 0x3b808081, v244
	v_rcp_f32_e32 v119, v119
	v_exp_f32_e32 v120, v120
	v_max_f32_e32 v118, 1.0, v118
	v_cvt_pk_u8_f32 v118, v118, 0, 0
	v_max_f32_e32 v119, 1.0, v119
	v_cvt_pk_u8_f32 v118, v119, 1, v118
	v_mul_f32_e32 v119, v72, v53
	v_fma_f32 v116, v116, v119, v169
	v_mul_f32_e32 v119, v52, v53
	v_fma_f32 v114, v114, v119, v168
	v_exp_f32_e32 v116, v116
	v_exp_f32_e32 v114, v114
	v_fmamk_f32 v51, v51, 0x3b808081, v244
	v_rcp_f32_e32 v51, v51
	v_fmamk_f32 v120, v120, 0x3b808081, v244
	v_rcp_f32_e32 v120, v120
	v_fmamk_f32 v116, v116, 0x3b808081, v244
	v_fmamk_f32 v114, v114, 0x3b808081, v244
	v_rcp_f32_e32 v116, v116
	v_rcp_f32_e32 v114, v114
	v_max_f32_e32 v51, 1.0, v51
	v_cvt_pk_u8_f32 v51, v51, 0, 0
	v_max_f32_e32 v120, 1.0, v120
	v_cvt_pk_u8_f32 v51, v120, 1, v51
	v_max_f32_e32 v116, 1.0, v116
	v_max_f32_e32 v114, 1.0, v114
	v_cvt_pk_u8_f32 v51, v116, 2, v51
	v_cvt_pk_u8_f32 v116, v114, 2, v118
	v_mul_f32_e32 v114, v56, v53
	v_fma_f32 v114, v117, v114, v151
	v_mul_f32_e32 v53, v50, v53
	v_exp_f32_e32 v114, v114
	v_fma_f32 v53, v115, v53, v149
	v_exp_f32_e32 v53, v53
	s_lshl_b64 s[0:1], s[0:1], 16
	v_fmamk_f32 v114, v114, 0x3b808081, v244
	v_rcp_f32_e32 v114, v114
	v_fmamk_f32 v53, v53, 0x3b808081, v244
	v_rcp_f32_e32 v53, v53
	v_cvt_pk_u8_f32 v158, v158, 0, 0
	v_max_f32_e32 v114, 1.0, v114
	v_cvt_pk_u8_f32 v114, v114, 3, v51
	v_max_f32_e32 v51, 1.0, v53
	v_cvt_pk_u8_f32 v115, v51, 3, v116
	v_mul_f32_e32 v51, v192, v71
	v_mul_f32_e32 v53, v190, v71
; __device__ __forceinline__ size_t g8_tile(int pm, int gt) { return ((size_t)pm * 24 + gt) * 65536; }
;     __device__ __forceinline__ void operator()(f32x4 (&acc)[2][2][4][2], const Unit& u, int wr, int wc, int fr, int fq) const {
;     ...
;             for (int ai = 0; ai < 2; ++ai)
; #pragma unroll
;                 for (int m = 0; m < 4; ++m) {
;                     const float s = sv[ai * 4 + m];
;                     u32x2 gb[2];
; #pragma unroll
;                     for (int bj = 0; bj < 2; ++bj) {
;                         const v4i_t i0 = __builtin_bit_cast(v4i_t, acc[ai][bj][m][0]), i1 = __builtin_bit_cast(v4i_t, acc[ai][bj][m][1]);
;                         unsigned w0 = 0u, w1 = 0u;
; #pragma unroll
;                         for (int j = 0; j < 4; ++j) {
;                             const float e0 = __builtin_amdgcn_exp2f(__builtin_fmaf((float)i0[j], s * cn[bj * 2][j], bn[bj * 2][j])), e1 = __builtin_amdgcn_exp2f(__builtin_fmaf((float)i1[j], s * cn[bj * 2 + 1][j], bn[bj * 2 + 1][j]));
;                             const float g0 = __builtin_amdgcn_rcpf(__builtin_fmaf(e0, 1.0f / 255.0f, 1.0f / 255.0f)), g1 = __builtin_amdgcn_rcpf(__builtin_fmaf(e1, 1.0f / 255.0f, 1.0f / 255.0f));
;                             w0 = __builtin_amdgcn_cvt_pk_u8_f32(fmaxf(g0, 1.0f), j, w0); w1 = __builtin_amdgcn_cvt_pk_u8_f32(fmaxf(g1, 1.0f), j, w1);
;                         }
;                         gb[bj].x = w0; gb[bj].y = w1;
;                     }
;                     unsigned char* gq = G8 + g8_tile(u.pm, u.pn - (C_GT - C_I8) / BM) + (wr * 4 + wc) * 8192 + (ai * 4 + m) * 1024 + (fq * 16 + fr) * 8;
;                     __builtin_nontemporal_store(gb[0], (u32x2*)gq); __builtin_nontemporal_store(gb[1], (u32x2*)(gq + 512));
	v_fma_f32 v51, v112, v51, v191
	v_fma_f32 v53, v110, v53, v189
	v_mul_f32_e32 v110, v188, v71
	v_exp_f32_e32 v51, v51
	v_fma_f32 v110, v113, v110, v187
	v_mul_f32_e32 v112, v186, v71
	v_exp_f32_e32 v53, v53
	v_exp_f32_e32 v110, v110
	v_fma_f32 v111, v111, v112, v185
	v_exp_f32_e32 v111, v111
	v_fmamk_f32 v51, v51, 0x3b808081, v244
	v_rcp_f32_e32 v51, v51
	v_fmamk_f32 v53, v53, 0x3b808081, v244
	v_fmamk_f32 v110, v110, 0x3b808081, v244
	v_rcp_f32_e32 v53, v53
	v_rcp_f32_e32 v110, v110
	v_fmamk_f32 v111, v111, 0x3b808081, v244
	v_rcp_f32_e32 v111, v111
	v_max_f32_e32 v51, 1.0, v51
	v_cvt_pk_u8_f32 v51, v51, 0, 0
	v_max_f32_e32 v53, 1.0, v53
	v_max_f32_e32 v110, 1.0, v110
	v_cvt_pk_u8_f32 v53, v53, 0, 0
	v_cvt_pk_u8_f32 v51, v110, 1, v51
	v_max_f32_e32 v110, 1.0, v111
	v_cvt_pk_u8_f32 v53, v110, 1, v53
	v_mul_f32_e32 v110, v183, v71
	v_fma_f32 v108, v108, v110, v182
	v_mul_f32_e32 v110, v181, v71
	v_fma_f32 v106, v106, v110, v180
	v_exp_f32_e32 v106, v106
	v_exp_f32_e32 v108, v108
	v_max_f32_e32 v159, 1.0, v159
	v_cvt_pk_u8_f32 v158, v159, 1, v158
	v_fmamk_f32 v106, v106, 0x3b808081, v244
	v_fmamk_f32 v108, v108, 0x3b808081, v244
	v_rcp_f32_e32 v106, v106
	v_rcp_f32_e32 v108, v108
	v_max_f32_e32 v154, 1.0, v154
	s_add_u32 s0, s97, s0
	v_max_f32_e32 v106, 1.0, v106
	v_max_f32_e32 v108, 1.0, v108
	v_cvt_pk_u8_f32 v53, v106, 2, v53
	v_mul_f32_e32 v106, v176, v71
	v_cvt_pk_u8_f32 v51, v108, 2, v51
	v_fma_f32 v106, v109, v106, v173
	v_mul_f32_e32 v108, v172, v71
	v_exp_f32_e32 v106, v106
	v_fma_f32 v107, v107, v108, v171
	v_exp_f32_e32 v107, v107
	v_cvt_pk_u8_f32 v154, v154, 2, v158
	v_fmamk_f32 v106, v106, 0x3b808081, v244
	v_rcp_f32_e32 v106, v106
	v_fmamk_f32 v107, v107, 0x3b808081, v244
	v_rcp_f32_e32 v107, v107
	v_max_f32_e32 v153, 1.0, v153
	v_max_f32_e32 v106, 1.0, v106
	v_cvt_pk_u8_f32 v106, v106, 3, v51
	v_max_f32_e32 v51, 1.0, v107
	v_cvt_pk_u8_f32 v107, v51, 3, v53
	v_mul_f32_e32 v51, v54, v71
	v_mul_f32_e32 v53, v78, v71
	v_fma_f32 v51, v104, v51, v184
	v_fma_f32 v53, v102, v53, v178
	v_mul_f32_e32 v102, v80, v71
	v_exp_f32_e32 v51, v51
	v_fma_f32 v102, v105, v102, v174
	v_mul_f32_e32 v104, v70, v71
	v_exp_f32_e32 v53, v53
	v_exp_f32_e32 v102, v102
	v_fma_f32 v103, v103, v104, v170
	v_exp_f32_e32 v103, v103
	v_fmamk_f32 v51, v51, 0x3b808081, v244
	v_rcp_f32_e32 v51, v51
	v_fmamk_f32 v53, v53, 0x3b808081, v244
	v_fmamk_f32 v102, v102, 0x3b808081, v244
	v_rcp_f32_e32 v53, v53
	v_rcp_f32_e32 v102, v102
	v_fmamk_f32 v103, v103, 0x3b808081, v244
	v_rcp_f32_e32 v103, v103
	v_max_f32_e32 v51, 1.0, v51
	v_cvt_pk_u8_f32 v51, v51, 0, 0
	v_max_f32_e32 v53, 1.0, v53
	v_max_f32_e32 v102, 1.0, v102
	v_cvt_pk_u8_f32 v53, v53, 0, 0
	v_cvt_pk_u8_f32 v51, v102, 1, v51
	v_max_f32_e32 v102, 1.0, v103
	v_cvt_pk_u8_f32 v53, v102, 1, v53
	v_mul_f32_e32 v102, v72, v71
	v_fma_f32 v100, v100, v102, v169
	v_mul_f32_e32 v102, v52, v71
	v_fma_f32 v98, v98, v102, v168
	v_exp_f32_e32 v98, v98
	v_exp_f32_e32 v100, v100
	s_addc_u32 s1, s29, s1
	v_cvt_pk_u8_f32 v154, v153, 3, v154
	v_fmamk_f32 v98, v98, 0x3b808081, v244
	v_rcp_f32_e32 v98, v98
	v_fmamk_f32 v100, v100, 0x3b808081, v244
	v_rcp_f32_e32 v100, v100
	v_lshl_add_u64 v[152:153], s[0:1], 0, v[142:143]
	v_max_f32_e32 v98, 1.0, v98
	v_cvt_pk_u8_f32 v53, v98, 2, v53
	v_mul_f32_e32 v98, v56, v71
	v_fma_f32 v98, v101, v98, v151
	v_mul_f32_e32 v71, v50, v71
	v_exp_f32_e32 v98, v98
	v_fma_f32 v71, v99, v71, v149
	v_exp_f32_e32 v71, v71
	v_max_f32_e32 v100, 1.0, v100
	v_fmamk_f32 v98, v98, 0x3b808081, v244
	v_rcp_f32_e32 v98, v98
	v_fmamk_f32 v71, v71, 0x3b808081, v244
	v_rcp_f32_e32 v71, v71
	v_cvt_pk_u8_f32 v51, v100, 2, v51
	v_max_f32_e32 v98, 1.0, v98
	v_cvt_pk_u8_f32 v98, v98, 3, v51
	v_max_f32_e32 v51, 1.0, v71
	v_cvt_pk_u8_f32 v99, v51, 3, v53
	v_mul_f32_e32 v51, v192, v79
	v_fma_f32 v51, v96, v51, v191
	v_mul_f32_e32 v53, v190, v79
	v_mul_f32_e32 v71, v188, v79
	v_exp_f32_e32 v51, v51
	v_fma_f32 v53, v94, v53, v189
	v_fma_f32 v71, v97, v71, v187
	v_mul_f32_e32 v94, v186, v79
	v_exp_f32_e32 v53, v53
	v_exp_f32_e32 v71, v71
	v_fma_f32 v94, v95, v94, v185
	v_exp_f32_e32 v94, v94
	v_fmamk_f32 v51, v51, 0x3b808081, v244
	v_rcp_f32_e32 v51, v51
	v_fmamk_f32 v53, v53, 0x3b808081, v244
	v_fmamk_f32 v71, v71, 0x3b808081, v244
	v_rcp_f32_e32 v53, v53
	v_rcp_f32_e32 v71, v71
	v_fmamk_f32 v94, v94, 0x3b808081, v244
	v_rcp_f32_e32 v94, v94
	v_max_f32_e32 v51, 1.0, v51
	v_cvt_pk_u8_f32 v51, v51, 0, 0
	v_max_f32_e32 v53, 1.0, v53
	v_max_f32_e32 v71, 1.0, v71
	v_cvt_pk_u8_f32 v53, v53, 0, 0
	v_cvt_pk_u8_f32 v51, v71, 1, v51
	v_max_f32_e32 v71, 1.0, v94
	v_cvt_pk_u8_f32 v53, v71, 1, v53
	v_mul_f32_e32 v71, v183, v79
	v_fma_f32 v71, v92, v71, v182
	v_mul_f32_e32 v92, v181, v79
	v_exp_f32_e32 v71, v71
	v_fma_f32 v90, v90, v92, v180
	v_exp_f32_e32 v90, v90
	s_mov_b64 s[0:1], 0x1000
	v_fmamk_f32 v71, v71, 0x3b808081, v244
	v_rcp_f32_e32 v71, v71
	v_fmamk_f32 v90, v90, 0x3b808081, v244
	v_rcp_f32_e32 v90, v90
	v_max_f32_e32 v161, 1.0, v161
	v_max_f32_e32 v71, 1.0, v71
	v_cvt_pk_u8_f32 v51, v71, 2, v51
	v_max_f32_e32 v71, 1.0, v90
	v_cvt_pk_u8_f32 v53, v71, 2, v53
	v_mul_f32_e32 v71, v176, v79
	v_fma_f32 v71, v93, v71, v173
	v_mul_f32_e32 v90, v172, v79
	v_exp_f32_e32 v71, v71
	v_fma_f32 v90, v91, v90, v171
	v_exp_f32_e32 v90, v90
	v_cvt_pk_u8_f32 v161, v161, 3, v164
	v_fmamk_f32 v71, v71, 0x3b808081, v244
	v_rcp_f32_e32 v71, v71
	v_fmamk_f32 v90, v90, 0x3b808081, v244
	v_rcp_f32_e32 v91, v90
	global_store_dwordx2 v[152:153], v[160:161], off nt
	global_store_dwordx2 v[152:153], v[154:155], off offset:512 nt
	v_max_f32_e32 v71, 1.0, v71
	v_cvt_pk_u8_f32 v90, v71, 3, v51
	v_max_f32_e32 v51, 1.0, v91
	v_cvt_pk_u8_f32 v91, v51, 3, v53
; __device__ __forceinline__ size_t g8_tile(int pm, int gt) { return ((size_t)pm * 24 + gt) * 65536; }
;     __device__ __forceinline__ void operator()(f32x4 (&acc)[2][2][4][2], const Unit& u, int wr, int wc, int fr, int fq) const {
;     ...
;             for (int ai = 0; ai < 2; ++ai)
; #pragma unroll
;                 for (int m = 0; m < 4; ++m) {
;                     const float s = sv[ai * 4 + m];
;                     u32x2 gb[2];
; #pragma unroll
;                     for (int bj = 0; bj < 2; ++bj) {
;                         const v4i_t i0 = __builtin_bit_cast(v4i_t, acc[ai][bj][m][0]), i1 = __builtin_bit_cast(v4i_t, acc[ai][bj][m][1]);
;                         unsigned w0 = 0u, w1 = 0u;
; #pragma unroll
;                         for (int j = 0; j < 4; ++j) {
;                             const float e0 = __builtin_amdgcn_exp2f(__builtin_fmaf((float)i0[j], s * cn[bj * 2][j], bn[bj * 2][j])), e1 = __builtin_amdgcn_exp2f(__builtin_fmaf((float)i1[j], s * cn[bj * 2 + 1][j], bn[bj * 2 + 1][j]));
;                             const float g0 = __builtin_amdgcn_rcpf(__builtin_fmaf(e0, 1.0f / 255.0f, 1.0f / 255.0f)), g1 = __builtin_amdgcn_rcpf(__builtin_fmaf(e1, 1.0f / 255.0f, 1.0f / 255.0f));
;                             w0 = __builtin_amdgcn_cvt_pk_u8_f32(fmaxf(g0, 1.0f), j, w0); w1 = __builtin_amdgcn_cvt_pk_u8_f32(fmaxf(g1, 1.0f), j, w1);
;                         }
;                         gb[bj].x = w0; gb[bj].y = w1;
;                     }
;                     unsigned char* gq = G8 + g8_tile(u.pm, u.pn - (C_GT - C_I8) / BM) + (wr * 4 + wc) * 8192 + (ai * 4 + m) * 1024 + (fq * 16 + fr) * 8;
;                     __builtin_nontemporal_store(gb[0], (u32x2*)gq); __builtin_nontemporal_store(gb[1], (u32x2*)(gq + 512));
	v_mul_f32_e32 v51, v54, v79
	v_fma_f32 v51, v88, v51, v184
	v_mul_f32_e32 v53, v78, v79
	v_mul_f32_e32 v71, v80, v79
	v_exp_f32_e32 v51, v51
	v_fma_f32 v53, v86, v53, v178
	v_fma_f32 v71, v89, v71, v174
	v_mul_f32_e32 v86, v70, v79
	v_exp_f32_e32 v53, v53
	v_exp_f32_e32 v71, v71
	v_fma_f32 v86, v87, v86, v170
	v_exp_f32_e32 v86, v86
	v_fmamk_f32 v51, v51, 0x3b808081, v244
	v_rcp_f32_e32 v51, v51
	v_fmamk_f32 v53, v53, 0x3b808081, v244
	v_fmamk_f32 v71, v71, 0x3b808081, v244
	v_rcp_f32_e32 v53, v53
	v_rcp_f32_e32 v71, v71
	v_fmamk_f32 v86, v86, 0x3b808081, v244
	v_rcp_f32_e32 v86, v86
	v_max_f32_e32 v51, 1.0, v51
	v_cvt_pk_u8_f32 v51, v51, 0, 0
	v_max_f32_e32 v53, 1.0, v53
	v_max_f32_e32 v71, 1.0, v71
	v_cvt_pk_u8_f32 v53, v53, 0, 0
	v_cvt_pk_u8_f32 v51, v71, 1, v51
	v_max_f32_e32 v71, 1.0, v86
	v_cvt_pk_u8_f32 v53, v71, 1, v53
	v_mul_f32_e32 v71, v72, v79
	v_fma_f32 v71, v84, v71, v169
	v_mul_f32_e32 v84, v52, v79
	v_exp_f32_e32 v71, v71
	v_fma_f32 v82, v82, v84, v168
	v_exp_f32_e32 v82, v82
	global_store_dwordx2 v[152:153], v[122:123], off offset:1024 nt
	global_store_dwordx2 v[152:153], v[114:115], off offset:1536 nt
	v_fmamk_f32 v71, v71, 0x3b808081, v244
	v_rcp_f32_e32 v71, v71
	v_fmamk_f32 v82, v82, 0x3b808081, v244
	v_rcp_f32_e32 v82, v82
	global_store_dwordx2 v[152:153], v[106:107], off offset:2048 nt
	global_store_dwordx2 v[152:153], v[98:99], off offset:2560 nt
	v_max_f32_e32 v71, 1.0, v71
	v_cvt_pk_u8_f32 v51, v71, 2, v51
	v_max_f32_e32 v71, 1.0, v82
	v_cvt_pk_u8_f32 v53, v71, 2, v53
	v_mul_f32_e32 v71, v56, v79
	v_fma_f32 v71, v85, v71, v151
	v_mul_f32_e32 v79, v50, v79
	v_exp_f32_e32 v71, v71
	v_fma_f32 v79, v83, v79, v149
	v_exp_f32_e32 v79, v79
	v_fmamk_f32 v71, v71, 0x3b808081, v244
	v_rcp_f32_e32 v71, v71
	v_fmamk_f32 v79, v79, 0x3b808081, v244
	v_rcp_f32_e32 v79, v79
	v_max_f32_e32 v71, 1.0, v71
	v_cvt_pk_u8_f32 v82, v71, 3, v51
	v_max_f32_e32 v51, 1.0, v79
	v_cvt_pk_u8_f32 v83, v51, 3, v53
	v_mul_f32_e32 v51, v192, v57
	v_fma_f32 v51, v76, v51, v191
	v_mul_f32_e32 v53, v190, v57
	v_mul_f32_e32 v71, v188, v57
	v_exp_f32_e32 v51, v51
	v_fma_f32 v53, v74, v53, v189
	v_fma_f32 v71, v77, v71, v187
	v_mul_f32_e32 v74, v186, v57
	v_exp_f32_e32 v53, v53
	v_exp_f32_e32 v71, v71
	v_fma_f32 v74, v75, v74, v185
	v_exp_f32_e32 v74, v74
	v_fmamk_f32 v51, v51, 0x3b808081, v244
	v_rcp_f32_e32 v51, v51
	v_fmamk_f32 v53, v53, 0x3b808081, v244
	v_fmamk_f32 v71, v71, 0x3b808081, v244
	v_rcp_f32_e32 v53, v53
	v_rcp_f32_e32 v71, v71
	v_fmamk_f32 v74, v74, 0x3b808081, v244
	v_rcp_f32_e32 v74, v74
	v_max_f32_e32 v51, 1.0, v51
	v_cvt_pk_u8_f32 v51, v51, 0, 0
	v_max_f32_e32 v53, 1.0, v53
	v_max_f32_e32 v71, 1.0, v71
	v_cvt_pk_u8_f32 v53, v53, 0, 0
	v_cvt_pk_u8_f32 v51, v71, 1, v51
	v_max_f32_e32 v71, 1.0, v74
	v_cvt_pk_u8_f32 v53, v71, 1, v53
	v_mul_f32_e32 v71, v183, v57
	v_fma_f32 v68, v68, v71, v182
	v_mul_f32_e32 v71, v181, v57
	v_fma_f32 v66, v66, v71, v180
	v_exp_f32_e32 v66, v66
	v_exp_f32_e32 v68, v68
	global_store_dwordx2 v[152:153], v[90:91], off offset:3072 nt
	global_store_dwordx2 v[152:153], v[82:83], off offset:3584 nt
	v_fmamk_f32 v66, v66, 0x3b808081, v244
	v_fmamk_f32 v68, v68, 0x3b808081, v244
	v_rcp_f32_e32 v66, v66
	v_rcp_f32_e32 v68, v68
	v_max_f32_e32 v66, 1.0, v66
	v_max_f32_e32 v68, 1.0, v68
	v_cvt_pk_u8_f32 v53, v66, 2, v53
	v_mul_f32_e32 v66, v176, v57
	v_cvt_pk_u8_f32 v51, v68, 2, v51
	v_fma_f32 v66, v69, v66, v173
	v_mul_f32_e32 v68, v172, v57
	v_exp_f32_e32 v66, v66
	v_fma_f32 v67, v67, v68, v171
	v_exp_f32_e32 v67, v67
	v_fmamk_f32 v66, v66, 0x3b808081, v244
	v_rcp_f32_e32 v66, v66
	v_fmamk_f32 v67, v67, 0x3b808081, v244
	v_rcp_f32_e32 v67, v67
	v_max_f32_e32 v66, 1.0, v66
	v_cvt_pk_u8_f32 v66, v66, 3, v51
	v_max_f32_e32 v51, 1.0, v67
	v_cvt_pk_u8_f32 v67, v51, 3, v53
	v_mul_f32_e32 v51, v54, v57
	v_mul_f32_e32 v53, v78, v57
	v_fma_f32 v51, v64, v51, v184
	v_fma_f32 v53, v62, v53, v178
	v_mul_f32_e32 v62, v80, v57
	v_exp_f32_e32 v51, v51
	v_fma_f32 v62, v65, v62, v174
	v_mul_f32_e32 v64, v70, v57
	v_exp_f32_e32 v53, v53
	v_exp_f32_e32 v62, v62
	v_fma_f32 v63, v63, v64, v170
	v_exp_f32_e32 v63, v63
	v_fmamk_f32 v51, v51, 0x3b808081, v244
	v_rcp_f32_e32 v51, v51
	v_fmamk_f32 v53, v53, 0x3b808081, v244
	v_fmamk_f32 v62, v62, 0x3b808081, v244
	v_rcp_f32_e32 v53, v53
	v_rcp_f32_e32 v62, v62
	v_fmamk_f32 v63, v63, 0x3b808081, v244
	v_rcp_f32_e32 v63, v63
	v_max_f32_e32 v51, 1.0, v51
	v_cvt_pk_u8_f32 v51, v51, 0, 0
	v_max_f32_e32 v53, 1.0, v53
	v_max_f32_e32 v62, 1.0, v62
	v_cvt_pk_u8_f32 v53, v53, 0, 0
	v_cvt_pk_u8_f32 v51, v62, 1, v51
	v_max_f32_e32 v62, 1.0, v63
	v_cvt_pk_u8_f32 v53, v62, 1, v53
	v_mul_f32_e32 v62, v72, v57
	v_fma_f32 v60, v60, v62, v169
	v_mul_f32_e32 v62, v52, v57
	v_fma_f32 v58, v58, v62, v168
	v_exp_f32_e32 v58, v58
	v_exp_f32_e32 v60, v60
	v_lshl_add_u64 v[62:63], v[152:153], 0, s[0:1]
	s_movk_i32 s0, 0x1000
	v_fmamk_f32 v58, v58, 0x3b808081, v244
	v_rcp_f32_e32 v58, v58
	v_fmamk_f32 v60, v60, 0x3b808081, v244
	v_rcp_f32_e32 v60, v60
	v_max_f32_e32 v58, 1.0, v58
	v_cvt_pk_u8_f32 v53, v58, 2, v53
	v_mul_f32_e32 v58, v56, v57
	v_fma_f32 v58, v61, v58, v151
	v_mul_f32_e32 v57, v50, v57
	v_exp_f32_e32 v58, v58
	v_fma_f32 v57, v59, v57, v149
	v_exp_f32_e32 v57, v57
	v_max_f32_e32 v60, 1.0, v60
	v_fmamk_f32 v58, v58, 0x3b808081, v244
	v_rcp_f32_e32 v58, v58
	v_fmamk_f32 v57, v57, 0x3b808081, v244
	v_rcp_f32_e32 v57, v57
	v_cvt_pk_u8_f32 v51, v60, 2, v51
	v_max_f32_e32 v58, 1.0, v58
	v_cvt_pk_u8_f32 v60, v58, 3, v51
	v_max_f32_e32 v51, 1.0, v57
	v_cvt_pk_u8_f32 v61, v51, 3, v53
	v_mul_f32_e32 v51, v192, v73
	v_fma_f32 v48, v48, v51, v191
	v_mul_f32_e32 v51, v190, v73
	v_fma_f32 v46, v46, v51, v189
; __device__ __forceinline__ size_t g8_tile(int pm, int gt) { return ((size_t)pm * 24 + gt) * 65536; }
;     __device__ __forceinline__ void operator()(f32x4 (&acc)[2][2][4][2], const Unit& u, int wr, int wc, int fr, int fq) const {
;     ...
;             for (int ai = 0; ai < 2; ++ai)
; #pragma unroll
;                 for (int m = 0; m < 4; ++m) {
;                     const float s = sv[ai * 4 + m];
;                     u32x2 gb[2];
; #pragma unroll
;                     for (int bj = 0; bj < 2; ++bj) {
;                         const v4i_t i0 = __builtin_bit_cast(v4i_t, acc[ai][bj][m][0]), i1 = __builtin_bit_cast(v4i_t, acc[ai][bj][m][1]);
;                         unsigned w0 = 0u, w1 = 0u;
; #pragma unroll
;                         for (int j = 0; j < 4; ++j) {
;                             const float e0 = __builtin_amdgcn_exp2f(__builtin_fmaf((float)i0[j], s * cn[bj * 2][j], bn[bj * 2][j])), e1 = __builtin_amdgcn_exp2f(__builtin_fmaf((float)i1[j], s * cn[bj * 2 + 1][j], bn[bj * 2 + 1][j]));
;                             const float g0 = __builtin_amdgcn_rcpf(__builtin_fmaf(e0, 1.0f / 255.0f, 1.0f / 255.0f)), g1 = __builtin_amdgcn_rcpf(__builtin_fmaf(e1, 1.0f / 255.0f, 1.0f / 255.0f));
;                             w0 = __builtin_amdgcn_cvt_pk_u8_f32(fmaxf(g0, 1.0f), j, w0); w1 = __builtin_amdgcn_cvt_pk_u8_f32(fmaxf(g1, 1.0f), j, w1);
;                         }
;                         gb[bj].x = w0; gb[bj].y = w1;
;                     }
;                     unsigned char* gq = G8 + g8_tile(u.pm, u.pn - (C_GT - C_I8) / BM) + (wr * 4 + wc) * 8192 + (ai * 4 + m) * 1024 + (fq * 16 + fr) * 8;
;                     __builtin_nontemporal_store(gb[0], (u32x2*)gq); __builtin_nontemporal_store(gb[1], (u32x2*)(gq + 512));
	v_mul_f32_e32 v51, v188, v73
	v_fma_f32 v49, v49, v51, v187
	v_mul_f32_e32 v51, v186, v73
	v_exp_f32_e32 v46, v46
	v_fma_f32 v47, v47, v51, v185
	v_exp_f32_e32 v47, v47
	v_exp_f32_e32 v48, v48
	v_fmamk_f32 v46, v46, 0x3b808081, v244
	v_rcp_f32_e32 v46, v46
	v_fmamk_f32 v47, v47, 0x3b808081, v244
	v_rcp_f32_e32 v47, v47
	v_exp_f32_e32 v49, v49
	v_max_f32_e32 v46, 1.0, v46
	v_cvt_pk_u8_f32 v46, v46, 0, 0
	v_max_f32_e32 v47, 1.0, v47
	v_cvt_pk_u8_f32 v46, v47, 1, v46
	v_mul_f32_e32 v47, v183, v73
	v_fma_f32 v44, v44, v47, v182
	v_mul_f32_e32 v47, v181, v73
	v_fma_f32 v42, v42, v47, v180
	v_exp_f32_e32 v42, v42
	v_exp_f32_e32 v44, v44
	v_fmamk_f32 v48, v48, 0x3b808081, v244
	v_rcp_f32_e32 v48, v48
	v_fmamk_f32 v42, v42, 0x3b808081, v244
	v_rcp_f32_e32 v42, v42
	v_fmamk_f32 v49, v49, 0x3b808081, v244
	v_rcp_f32_e32 v49, v49
	v_fmamk_f32 v44, v44, 0x3b808081, v244
	v_max_f32_e32 v42, 1.0, v42
	v_cvt_pk_u8_f32 v46, v42, 2, v46
	v_mul_f32_e32 v42, v176, v73
	v_fma_f32 v42, v45, v42, v173
	v_exp_f32_e32 v42, v42
	v_rcp_f32_e32 v44, v44
	v_max_f32_e32 v48, 1.0, v48
	v_cvt_pk_u8_f32 v48, v48, 0, 0
	v_fmamk_f32 v42, v42, 0x3b808081, v244
	v_rcp_f32_e32 v42, v42
	v_max_f32_e32 v49, 1.0, v49
	v_cvt_pk_u8_f32 v48, v49, 1, v48
	v_max_f32_e32 v44, 1.0, v44
	v_cvt_pk_u8_f32 v44, v44, 2, v48
	v_max_f32_e32 v42, 1.0, v42
	v_cvt_pk_u8_f32 v42, v42, 3, v44
	v_mul_f32_e32 v44, v54, v73
	v_fma_f32 v38, v38, v44, v184
	v_mul_f32_e32 v44, v78, v73
	v_fma_f32 v34, v34, v44, v178
	v_mul_f32_e32 v44, v80, v73
	v_fma_f32 v39, v39, v44, v174
	v_mul_f32_e32 v44, v70, v73
	v_exp_f32_e32 v34, v34
	v_fma_f32 v35, v35, v44, v170
	v_exp_f32_e32 v35, v35
	v_exp_f32_e32 v38, v38
	v_fmamk_f32 v34, v34, 0x3b808081, v244
	v_exp_f32_e32 v39, v39
	v_rcp_f32_e32 v34, v34
	v_fmamk_f32 v35, v35, 0x3b808081, v244
	v_rcp_f32_e32 v35, v35
	v_fmamk_f32 v38, v38, 0x3b808081, v244
	v_rcp_f32_e32 v38, v38
	v_fmamk_f32 v39, v39, 0x3b808081, v244
	v_max_f32_e32 v34, 1.0, v34
	v_rcp_f32_e32 v39, v39
	v_cvt_pk_u8_f32 v34, v34, 0, 0
	v_max_f32_e32 v35, 1.0, v35
	v_cvt_pk_u8_f32 v34, v35, 1, v34
	v_cvt_f32_i32_e32 v35, v40
	v_max_f32_e32 v38, 1.0, v38
	v_cvt_pk_u8_f32 v38, v38, 0, 0
	v_max_f32_e32 v39, 1.0, v39
	v_cvt_pk_u8_f32 v38, v39, 1, v38
	v_mul_f32_e32 v39, v72, v73
	v_fma_f32 v35, v35, v39, v169
	v_mul_f32_e32 v39, v52, v73
	v_fma_f32 v36, v36, v39, v168
	v_exp_f32_e32 v36, v36
	v_exp_f32_e32 v35, v35
	v_mul_f32_e32 v45, v172, v73
	v_fma_f32 v43, v43, v45, v171
	v_fmamk_f32 v36, v36, 0x3b808081, v244
	v_rcp_f32_e32 v36, v36
	v_fmamk_f32 v35, v35, 0x3b808081, v244
	v_rcp_f32_e32 v35, v35
	v_exp_f32_e32 v43, v43
	v_max_f32_e32 v36, 1.0, v36
	v_cvt_pk_u8_f32 v36, v36, 2, v34
	v_cvt_f32_i32_e32 v34, v41
	v_max_f32_e32 v35, 1.0, v35
	v_cvt_pk_u8_f32 v35, v35, 2, v38
	v_mul_f32_e32 v38, v56, v73
	v_fma_f32 v34, v34, v38, v151
	v_mul_f32_e32 v38, v50, v73
	v_exp_f32_e32 v34, v34
	v_fma_f32 v37, v37, v38, v149
	v_exp_f32_e32 v37, v37
	v_fmamk_f32 v43, v43, 0x3b808081, v244
	v_fmamk_f32 v34, v34, 0x3b808081, v244
	v_rcp_f32_e32 v43, v43
	v_rcp_f32_e32 v34, v34
	v_fmamk_f32 v37, v37, 0x3b808081, v244
	v_rcp_f32_e32 v37, v37
	v_add_co_u32_e32 v58, vcc, s0, v152
	v_max_f32_e32 v43, 1.0, v43
	v_max_f32_e32 v34, 1.0, v34
	v_addc_co_u32_e32 v59, vcc, 0, v153, vcc
	v_cvt_pk_u8_f32 v43, v43, 3, v46
	v_cvt_pk_u8_f32 v34, v34, 3, v35
	v_max_f32_e32 v35, 1.0, v37
	s_mov_b64 s[0:1], 0x1400
	global_store_dwordx2 v[58:59], v[66:67], off nt
	global_store_dwordx2 v[62:63], v[60:61], off offset:512 nt
	v_cvt_pk_u8_f32 v35, v35, 3, v36
	v_lshl_add_u64 v[36:37], v[152:153], 0, s[0:1]
	global_store_dwordx2 v[58:59], v[42:43], off offset:1024 nt
	global_store_dwordx2 v[36:37], v[34:35], off offset:512 nt
	v_mul_f32_e32 v34, v192, v81
	v_fma_f32 v30, v30, v34, v191
	v_mul_f32_e32 v34, v190, v81
	v_fma_f32 v26, v26, v34, v189
	v_mul_f32_e32 v34, v188, v81
	v_fma_f32 v31, v31, v34, v187
	v_mul_f32_e32 v34, v186, v81
	v_exp_f32_e32 v26, v26
	v_fma_f32 v27, v27, v34, v185
	v_exp_f32_e32 v27, v27
	v_exp_f32_e32 v30, v30
	v_fmamk_f32 v26, v26, 0x3b808081, v244
	v_exp_f32_e32 v31, v31
	v_rcp_f32_e32 v26, v26
	v_fmamk_f32 v27, v27, 0x3b808081, v244
	v_rcp_f32_e32 v27, v27
	v_fmamk_f32 v30, v30, 0x3b808081, v244
	v_rcp_f32_e32 v30, v30
	v_fmamk_f32 v31, v31, 0x3b808081, v244
	v_max_f32_e32 v26, 1.0, v26
	v_rcp_f32_e32 v31, v31
	v_cvt_pk_u8_f32 v26, v26, 0, 0
	v_max_f32_e32 v27, 1.0, v27
	v_cvt_pk_u8_f32 v26, v27, 1, v26
	v_cvt_f32_i32_e32 v27, v32
	v_max_f32_e32 v30, 1.0, v30
	v_cvt_pk_u8_f32 v30, v30, 0, 0
	v_max_f32_e32 v31, 1.0, v31
	v_cvt_pk_u8_f32 v30, v31, 1, v30
	v_mul_f32_e32 v31, v183, v81
	v_fma_f32 v27, v27, v31, v182
	v_mul_f32_e32 v31, v181, v81
	v_fma_f32 v28, v28, v31, v180
	v_exp_f32_e32 v28, v28
	v_exp_f32_e32 v27, v27
	s_mov_b64 s[0:1], 0x1800
	v_fmamk_f32 v28, v28, 0x3b808081, v244
	v_rcp_f32_e32 v28, v28
	v_fmamk_f32 v27, v27, 0x3b808081, v244
	v_rcp_f32_e32 v27, v27
	v_max_f32_e32 v28, 1.0, v28
	v_cvt_pk_u8_f32 v28, v28, 2, v26
	v_cvt_f32_i32_e32 v26, v33
	v_max_f32_e32 v27, 1.0, v27
	v_cvt_pk_u8_f32 v27, v27, 2, v30
	v_mul_f32_e32 v30, v176, v81
	v_fma_f32 v26, v26, v30, v173
	v_mul_f32_e32 v30, v172, v81
	v_exp_f32_e32 v26, v26
	v_fma_f32 v29, v29, v30, v171
	v_exp_f32_e32 v29, v29
	v_fmamk_f32 v26, v26, 0x3b808081, v244
	v_rcp_f32_e32 v26, v26
	v_fmamk_f32 v29, v29, 0x3b808081, v244
	v_rcp_f32_e32 v29, v29
	v_max_f32_e32 v26, 1.0, v26
	v_cvt_pk_u8_f32 v26, v26, 3, v27
	v_max_f32_e32 v27, 1.0, v29
	v_cvt_pk_u8_f32 v27, v27, 3, v28
	v_mul_f32_e32 v28, v54, v81
; __device__ __forceinline__ size_t g8_tile(int pm, int gt) { return ((size_t)pm * 24 + gt) * 65536; }
;     __device__ __forceinline__ void operator()(f32x4 (&acc)[2][2][4][2], const Unit& u, int wr, int wc, int fr, int fq) const {
;     ...
;             for (int ai = 0; ai < 2; ++ai)
; #pragma unroll
;                 for (int m = 0; m < 4; ++m) {
;                     const float s = sv[ai * 4 + m];
;                     u32x2 gb[2];
; #pragma unroll
;                     for (int bj = 0; bj < 2; ++bj) {
;                         const v4i_t i0 = __builtin_bit_cast(v4i_t, acc[ai][bj][m][0]), i1 = __builtin_bit_cast(v4i_t, acc[ai][bj][m][1]);
;                         unsigned w0 = 0u, w1 = 0u;
; #pragma unroll
;                         for (int j = 0; j < 4; ++j) {
;                             const float e0 = __builtin_amdgcn_exp2f(__builtin_fmaf((float)i0[j], s * cn[bj * 2][j], bn[bj * 2][j])), e1 = __builtin_amdgcn_exp2f(__builtin_fmaf((float)i1[j], s * cn[bj * 2 + 1][j], bn[bj * 2 + 1][j]));
;                             const float g0 = __builtin_amdgcn_rcpf(__builtin_fmaf(e0, 1.0f / 255.0f, 1.0f / 255.0f)), g1 = __builtin_amdgcn_rcpf(__builtin_fmaf(e1, 1.0f / 255.0f, 1.0f / 255.0f));
;                             w0 = __builtin_amdgcn_cvt_pk_u8_f32(fmaxf(g0, 1.0f), j, w0); w1 = __builtin_amdgcn_cvt_pk_u8_f32(fmaxf(g1, 1.0f), j, w1);
;                         }
;                         gb[bj].x = w0; gb[bj].y = w1;
;                     }
;                     unsigned char* gq = G8 + g8_tile(u.pm, u.pn - (C_GT - C_I8) / BM) + (wr * 4 + wc) * 8192 + (ai * 4 + m) * 1024 + (fq * 16 + fr) * 8;
;                     __builtin_nontemporal_store(gb[0], (u32x2*)gq); __builtin_nontemporal_store(gb[1], (u32x2*)(gq + 512));
	v_fma_f32 v22, v22, v28, v184
	v_mul_f32_e32 v28, v78, v81
	v_fma_f32 v18, v18, v28, v178
	v_mul_f32_e32 v28, v80, v81
	v_fma_f32 v23, v23, v28, v174
	v_mul_f32_e32 v28, v70, v81
	v_exp_f32_e32 v18, v18
	v_fma_f32 v19, v19, v28, v170
	v_exp_f32_e32 v19, v19
	v_exp_f32_e32 v22, v22
	v_fmamk_f32 v18, v18, 0x3b808081, v244
	v_exp_f32_e32 v23, v23
	v_rcp_f32_e32 v18, v18
	v_fmamk_f32 v19, v19, 0x3b808081, v244
	v_rcp_f32_e32 v19, v19
	v_fmamk_f32 v22, v22, 0x3b808081, v244
	v_rcp_f32_e32 v22, v22
	v_fmamk_f32 v23, v23, 0x3b808081, v244
	v_max_f32_e32 v18, 1.0, v18
	v_rcp_f32_e32 v23, v23
	v_cvt_pk_u8_f32 v18, v18, 0, 0
	v_max_f32_e32 v19, 1.0, v19
	v_cvt_pk_u8_f32 v18, v19, 1, v18
	v_cvt_f32_i32_e32 v19, v24
	v_max_f32_e32 v22, 1.0, v22
	v_cvt_pk_u8_f32 v22, v22, 0, 0
	v_max_f32_e32 v23, 1.0, v23
	v_cvt_pk_u8_f32 v22, v23, 1, v22
	v_mul_f32_e32 v23, v72, v81
	v_fma_f32 v19, v19, v23, v169
	v_mul_f32_e32 v23, v52, v81
	v_fma_f32 v20, v20, v23, v168
	v_exp_f32_e32 v20, v20
	v_exp_f32_e32 v19, v19
	v_fmamk_f32 v20, v20, 0x3b808081, v244
	v_rcp_f32_e32 v20, v20
	v_fmamk_f32 v19, v19, 0x3b808081, v244
	v_rcp_f32_e32 v19, v19
	v_max_f32_e32 v20, 1.0, v20
	v_cvt_pk_u8_f32 v20, v20, 2, v18
	v_cvt_f32_i32_e32 v18, v25
	v_max_f32_e32 v19, 1.0, v19
	v_cvt_pk_u8_f32 v19, v19, 2, v22
	v_mul_f32_e32 v22, v56, v81
	v_fma_f32 v18, v18, v22, v151
	v_mul_f32_e32 v22, v50, v81
	v_exp_f32_e32 v18, v18
	v_fma_f32 v21, v21, v22, v149
	v_exp_f32_e32 v21, v21
	v_fmamk_f32 v18, v18, 0x3b808081, v244
	v_rcp_f32_e32 v18, v18
	v_fmamk_f32 v21, v21, 0x3b808081, v244
	v_rcp_f32_e32 v21, v21
	v_max_f32_e32 v18, 1.0, v18
	v_cvt_pk_u8_f32 v18, v18, 3, v19
	v_max_f32_e32 v19, 1.0, v21
	v_cvt_pk_u8_f32 v19, v19, 3, v20
	v_lshl_add_u64 v[20:21], v[152:153], 0, s[0:1]
	global_store_dwordx2 v[58:59], v[26:27], off offset:2048 nt
	global_store_dwordx2 v[20:21], v[18:19], off offset:512 nt
	v_mul_f32_e32 v18, v192, v55
	v_fmac_f32_e32 v191, v14, v18
	v_mul_f32_e32 v18, v190, v55
	v_fmac_f32_e32 v189, v10, v18
	v_mul_f32_e32 v18, v188, v55
	v_fmac_f32_e32 v187, v15, v18
	v_mul_f32_e32 v18, v186, v55
	v_exp_f32_e32 v10, v189
	v_fmac_f32_e32 v185, v11, v18
	v_exp_f32_e32 v11, v185
	v_exp_f32_e32 v14, v191
	v_fmamk_f32 v10, v10, 0x3b808081, v244
	v_exp_f32_e32 v15, v187
	v_rcp_f32_e32 v10, v10
	v_fmamk_f32 v11, v11, 0x3b808081, v244
	v_rcp_f32_e32 v11, v11
	v_fmamk_f32 v14, v14, 0x3b808081, v244
	v_rcp_f32_e32 v14, v14
	v_fmamk_f32 v15, v15, 0x3b808081, v244
	v_max_f32_e32 v10, 1.0, v10
	v_rcp_f32_e32 v15, v15
	v_cvt_pk_u8_f32 v10, v10, 0, 0
	v_max_f32_e32 v11, 1.0, v11
	v_cvt_pk_u8_f32 v10, v11, 1, v10
	v_cvt_f32_i32_e32 v11, v16
	v_max_f32_e32 v14, 1.0, v14
	v_cvt_pk_u8_f32 v14, v14, 0, 0
	v_max_f32_e32 v15, 1.0, v15
	v_cvt_pk_u8_f32 v14, v15, 1, v14
	v_mul_f32_e32 v15, v183, v55
	v_fmac_f32_e32 v182, v11, v15
	v_mul_f32_e32 v15, v181, v55
	v_fmac_f32_e32 v180, v12, v15
	v_exp_f32_e32 v12, v180
	v_exp_f32_e32 v11, v182
	s_mov_b64 s[0:1], 0x1c00
	v_fmamk_f32 v12, v12, 0x3b808081, v244
	v_rcp_f32_e32 v12, v12
	v_fmamk_f32 v11, v11, 0x3b808081, v244
	v_rcp_f32_e32 v11, v11
	v_max_f32_e32 v12, 1.0, v12
	v_cvt_pk_u8_f32 v12, v12, 2, v10
	v_cvt_f32_i32_e32 v10, v17
	v_max_f32_e32 v11, 1.0, v11
	v_cvt_pk_u8_f32 v11, v11, 2, v14
	v_mul_f32_e32 v14, v176, v55
	v_fmac_f32_e32 v173, v10, v14
	v_mul_f32_e32 v14, v172, v55
	v_exp_f32_e32 v10, v173
	v_fmac_f32_e32 v171, v13, v14
	v_exp_f32_e32 v13, v171
	v_fmamk_f32 v10, v10, 0x3b808081, v244
	v_rcp_f32_e32 v10, v10
	v_fmamk_f32 v13, v13, 0x3b808081, v244
	v_rcp_f32_e32 v13, v13
	v_max_f32_e32 v10, 1.0, v10
	v_cvt_pk_u8_f32 v10, v10, 3, v11
	v_max_f32_e32 v11, 1.0, v13
	v_cvt_pk_u8_f32 v11, v11, 3, v12
	v_mul_f32_e32 v12, v54, v55
	v_fmac_f32_e32 v184, v6, v12
	v_mul_f32_e32 v12, v78, v55
	v_fmac_f32_e32 v178, v2, v12
	v_mul_f32_e32 v12, v80, v55
	v_fmac_f32_e32 v174, v7, v12
	v_mul_f32_e32 v12, v70, v55
	v_exp_f32_e32 v2, v178
	v_fmac_f32_e32 v170, v3, v12
	v_exp_f32_e32 v3, v170
	v_exp_f32_e32 v6, v184
	v_fmamk_f32 v2, v2, 0x3b808081, v244
	v_exp_f32_e32 v7, v174
	v_rcp_f32_e32 v2, v2
	v_fmamk_f32 v3, v3, 0x3b808081, v244
	v_rcp_f32_e32 v3, v3
	v_fmamk_f32 v6, v6, 0x3b808081, v244
	v_rcp_f32_e32 v6, v6
	v_fmamk_f32 v7, v7, 0x3b808081, v244
	v_max_f32_e32 v2, 1.0, v2
	v_rcp_f32_e32 v7, v7
	v_cvt_pk_u8_f32 v2, v2, 0, 0
	v_max_f32_e32 v3, 1.0, v3
	v_cvt_pk_u8_f32 v2, v3, 1, v2
	v_cvt_f32_i32_e32 v3, v8
	v_max_f32_e32 v6, 1.0, v6
	v_cvt_pk_u8_f32 v6, v6, 0, 0
	v_max_f32_e32 v7, 1.0, v7
	v_cvt_pk_u8_f32 v6, v7, 1, v6
	v_mul_f32_e32 v7, v72, v55
	v_fmac_f32_e32 v169, v3, v7
	v_mul_f32_e32 v7, v52, v55
	v_fmac_f32_e32 v168, v4, v7
	v_exp_f32_e32 v4, v168
	v_exp_f32_e32 v3, v169
	v_fmamk_f32 v4, v4, 0x3b808081, v244
	v_rcp_f32_e32 v4, v4
	v_fmamk_f32 v3, v3, 0x3b808081, v244
	v_rcp_f32_e32 v3, v3
	v_max_f32_e32 v4, 1.0, v4
	v_cvt_pk_u8_f32 v4, v4, 2, v2
	v_cvt_f32_i32_e32 v2, v9
	v_max_f32_e32 v3, 1.0, v3
	v_cvt_pk_u8_f32 v3, v3, 2, v6
	v_mul_f32_e32 v6, v56, v55
	v_fmac_f32_e32 v151, v2, v6
	v_mul_f32_e32 v6, v50, v55
	v_exp_f32_e32 v2, v151
	v_fmac_f32_e32 v149, v5, v6
	v_exp_f32_e32 v5, v149
	v_fmamk_f32 v2, v2, 0x3b808081, v244
	v_rcp_f32_e32 v2, v2
	v_fmamk_f32 v5, v5, 0x3b808081, v244
	v_rcp_f32_e32 v5, v5
	v_max_f32_e32 v2, 1.0, v2
	v_cvt_pk_u8_f32 v2, v2, 3, v3
	v_max_f32_e32 v3, 1.0, v5
	v_cvt_pk_u8_f32 v3, v3, 3, v4
	v_lshl_add_u64 v[4:5], v[152:153], 0, s[0:1]
	global_store_dwordx2 v[58:59], v[10:11], off offset:3072 nt
	global_store_dwordx2 v[4:5], v[2:3], off offset:512 nt
